# s=2: attn unit issues an L2 warm-up of the next slot's conv-unit PROJ rows (two unused dword loads per thread), on top of v9
# speedup vs baseline: 1.0024x; 1.0024x over previous
.LBB0_468:
	s_or_b64 exec, exec, s[20:21]
	v_readlane_b32 s20, v253, 25
	s_nop 0
	s_cmp_lt_i32 s20, 4
	s_cbranch_scc0 .Lattn_nopf
	v_readlane_b32 s20, v253, 28
	s_nop 0
	s_lshr_b32 s21, s20, 6
	s_lshl_b32 s21, s21, 12
	s_and_b32 s20, s20, 63
	s_lshl_b32 s20, s20, 6
	s_add_i32 s20, s20, s21
	s_sub_i32 s20, s20, 30
	s_mul_i32 s20, s20, 0x1800
	s_ashr_i32 s21, s20, 31
	v_readlane_b32 s98, v250, 62
	v_readlane_b32 s99, v250, 63
	s_nop 0
	s_add_u32 s98, s98, s20
	s_addc_u32 s99, s99, s21
	s_add_u32 s98, s98, 0x5b00000
	s_addc_u32 s99, s99, 0
	v_readlane_b32 s20, v251, 7
	s_nop 1
	v_add_u32_e32 v178, s20, v226
	v_lshrrev_b32_e32 v179, 3, v178
	v_mul_u32_u24_e32 v179, 0x1800, v179
	v_and_b32_e32 v178, 7, v178
	v_lshl_add_u32 v178, v178, 7, v179
	global_load_dword v180, v178, s[98:99]
	v_add_u32_e32 v178, 0x60000, v178
	global_load_dword v180, v178, s[98:99]
.Lattn_nopf:
	v_add_u32_e32 v98, 0x8480, v152
	v_add_u32_e32 v100, 0x8488, v152
	v_add_u32_e32 v102, 0x84a0, v152
	v_add_u32_e32 v104, 0x84a8, v152
	s_waitcnt lgkmcnt(0)
	s_barrier
	ds_read2_b32 v[98:99], v98 offset1:1
	ds_read2_b32 v[100:101], v100 offset1:1
	ds_read2_b32 v[102:103], v102 offset1:1
	ds_read2_b32 v[104:105], v104 offset1:1
	v_readlane_b32 s20, v253, 47
	v_add_u32_e32 v106, 0x84c0, v152
	v_add_u32_e32 v108, 0x84c8, v152
	v_add_u32_e32 v110, 0x84e0, v152
	v_add_u32_e32 v112, 0x84e8, v152
	v_readlane_b32 s21, v253, 48
	ds_read2_b32 v[106:107], v106 offset1:1
	ds_read2_b32 v[108:109], v108 offset1:1
	ds_read2_b32 v[110:111], v110 offset1:1
	ds_read2_b32 v[112:113], v112 offset1:1
	s_waitcnt lgkmcnt(6)
	s_and_b64 vcc, s[20:21], s[44:45]
	v_readlane_b32 s20, v253, 49
	v_fmac_f32_e32 v98, 0x3e000000, v64
	v_readlane_b32 s21, v253, 50
	v_cndmask_b32_e32 v64, v228, v98, vcc
	v_fmac_f32_e32 v99, 0x3e000000, v65
	s_and_b64 vcc, s[20:21], s[44:45]
	v_cndmask_b32_e32 v65, v228, v99, vcc
	s_mov_b32 s20, 0xff800000
	v_max3_f32 v98, v64, s20, v65
	v_readlane_b32 s20, v253, 51
	v_readlane_b32 s21, v253, 52
	s_and_b64 vcc, s[20:21], s[44:45]
	v_readlane_b32 s20, v253, 53
	v_fmac_f32_e32 v100, 0x3e000000, v66
	v_readlane_b32 s21, v253, 54
	v_cndmask_b32_e32 v66, v228, v100, vcc
	s_and_b64 vcc, s[20:21], s[44:45]
	v_readlane_b32 s20, v253, 55
	v_fmac_f32_e32 v101, 0x3e000000, v67
	v_readlane_b32 s21, v253, 56
	s_waitcnt lgkmcnt(4)
	v_cndmask_b32_e32 v67, v228, v101, vcc
	s_and_b64 vcc, s[20:21], s[44:45]
	v_readlane_b32 s20, v253, 57
	v_fmac_f32_e32 v102, 0x3e000000, v68
	v_readlane_b32 s21, v253, 58
	v_cndmask_b32_e32 v68, v228, v102, vcc
	s_and_b64 vcc, s[20:21], s[44:45]
	v_readlane_b32 s20, v253, 59
	v_fmac_f32_e32 v103, 0x3e000000, v69
	v_readlane_b32 s21, v253, 60
	v_cndmask_b32_e32 v69, v228, v103, vcc
	s_and_b64 vcc, s[20:21], s[44:45]
	v_readlane_b32 s20, v253, 61
	v_fmac_f32_e32 v104, 0x3e000000, v70
	v_readlane_b32 s21, v253, 62
	v_cndmask_b32_e32 v70, v228, v104, vcc
	s_and_b64 vcc, s[20:21], s[44:45]
	v_readlane_b32 s20, v253, 63
	v_fmac_f32_e32 v105, 0x3e000000, v71
	v_readlane_b32 s21, v254, 0
	s_waitcnt lgkmcnt(2)
	v_cndmask_b32_e32 v71, v228, v105, vcc
	s_and_b64 vcc, s[20:21], s[44:45]
	v_readlane_b32 s20, v254, 1
	v_fmac_f32_e32 v106, 0x3e000000, v72
	v_readlane_b32 s21, v254, 2
	v_cndmask_b32_e32 v72, v228, v106, vcc
	s_and_b64 vcc, s[20:21], s[44:45]
	v_readlane_b32 s20, v254, 3
	v_fmac_f32_e32 v107, 0x3e000000, v73
	v_readlane_b32 s21, v254, 4
	v_cndmask_b32_e32 v73, v228, v107, vcc
	s_and_b64 vcc, s[20:21], s[44:45]
	v_readlane_b32 s20, v254, 5
	v_fmac_f32_e32 v108, 0x3e000000, v74
	v_readlane_b32 s21, v254, 6
	v_max3_f32 v98, v98, v66, v67
	v_cndmask_b32_e32 v74, v228, v108, vcc
	s_and_b64 vcc, s[20:21], s[44:45]
	v_readlane_b32 s20, v254, 7
	v_max3_f32 v98, v98, v68, v69
	v_fmac_f32_e32 v109, 0x3e000000, v75
	v_readlane_b32 s21, v254, 8
	s_waitcnt lgkmcnt(0)
	v_max3_f32 v98, v98, v70, v71
	v_cndmask_b32_e32 v75, v228, v109, vcc
	s_and_b64 vcc, s[20:21], s[44:45]
	v_readlane_b32 s20, v254, 9
	v_max3_f32 v98, v98, v72, v73
	v_fmac_f32_e32 v110, 0x3e000000, v76
	v_readlane_b32 s21, v254, 10
	v_max3_f32 v99, v98, v74, v75
	v_cndmask_b32_e32 v98, v228, v110, vcc
	s_and_b64 vcc, s[20:21], s[44:45]
	v_readlane_b32 s20, v254, 11
	v_fmac_f32_e32 v111, 0x3e000000, v77
	v_readlane_b32 s21, v254, 12
	v_cndmask_b32_e32 v77, v228, v111, vcc
	s_and_b64 vcc, s[20:21], s[44:45]
	v_readlane_b32 s20, v254, 13
	v_fmac_f32_e32 v112, 0x3e000000, v78
	v_readlane_b32 s21, v254, 14
	v_cndmask_b32_e32 v78, v228, v112, vcc
	v_fmac_f32_e32 v113, 0x3e000000, v79
	s_and_b64 vcc, s[20:21], s[44:45]
	v_max3_f32 v99, v99, v98, v77
	v_cndmask_b32_e32 v76, v228, v113, vcc
	v_max3_f32 v99, v99, v78, v76
	v_add_u32_e32 v79, 0x8500, v152
	v_add_u32_e32 v102, 0x8508, v152
	v_add_u32_e32 v104, 0x8520, v152
	v_add_u32_e32 v106, 0x8528, v152
	ds_read2_b32 v[100:101], v79 offset1:1
	ds_read2_b32 v[102:103], v102 offset1:1
	ds_read2_b32 v[104:105], v104 offset1:1
	ds_read2_b32 v[106:107], v106 offset1:1
	v_readlane_b32 s20, v254, 15
	v_add_u32_e32 v79, 0x8540, v152
	v_add_u32_e32 v110, 0x8548, v152
	v_add_u32_e32 v112, 0x8560, v152
	v_add_u32_e32 v114, 0x8568, v152
	v_readlane_b32 s21, v254, 16
	ds_read2_b32 v[108:109], v79 offset1:1
	ds_read2_b32 v[110:111], v110 offset1:1
	ds_read2_b32 v[112:113], v112 offset1:1
	ds_read2_b32 v[114:115], v114 offset1:1
	s_waitcnt lgkmcnt(6)
	s_or_b64 vcc, s[44:45], s[20:21]
	v_readlane_b32 s20, v254, 17
	v_fmac_f32_e32 v100, 0x3e000000, v48
	v_readlane_b32 s21, v254, 18
	v_cndmask_b32_e32 v79, v228, v100, vcc
	s_or_b64 vcc, s[44:45], s[20:21]
	v_readlane_b32 s20, v254, 19
	v_fmac_f32_e32 v101, 0x3e000000, v49
	v_readlane_b32 s21, v254, 20
	v_cndmask_b32_e32 v49, v228, v101, vcc
	s_or_b64 vcc, s[44:45], s[20:21]
	v_readlane_b32 s20, v254, 21
	v_fmac_f32_e32 v102, 0x3e000000, v50
	v_readlane_b32 s21, v254, 22
	v_cndmask_b32_e32 v50, v228, v102, vcc
	s_or_b64 vcc, s[44:45], s[20:21]
	v_readlane_b32 s20, v254, 23
	v_fmac_f32_e32 v103, 0x3e000000, v51
	v_readlane_b32 s21, v254, 24
	s_waitcnt lgkmcnt(4)
	v_cndmask_b32_e32 v51, v228, v103, vcc
	s_or_b64 vcc, s[44:45], s[20:21]
	v_readlane_b32 s20, v254, 25
	v_fmac_f32_e32 v104, 0x3e000000, v52
	v_readlane_b32 s21, v254, 26
	v_cndmask_b32_e32 v52, v228, v104, vcc
	s_or_b64 vcc, s[44:45], s[20:21]
	v_readlane_b32 s20, v254, 27
	v_fmac_f32_e32 v105, 0x3e000000, v53
	v_readlane_b32 s21, v254, 28
	v_cndmask_b32_e32 v53, v228, v105, vcc
	s_or_b64 vcc, s[44:45], s[20:21]
	v_readlane_b32 s20, v254, 29
	v_fmac_f32_e32 v106, 0x3e000000, v54
	v_readlane_b32 s21, v254, 30
	v_max3_f32 v48, v99, v79, v49
	v_cndmask_b32_e32 v99, v228, v106, vcc
	s_or_b64 vcc, s[44:45], s[20:21]
	v_readlane_b32 s20, v254, 31
	v_fmac_f32_e32 v107, 0x3e000000, v55
	v_readlane_b32 s21, v254, 32
	s_waitcnt lgkmcnt(2)
	v_cndmask_b32_e32 v55, v228, v107, vcc
	s_or_b64 vcc, s[44:45], s[20:21]
	v_readlane_b32 s20, v254, 33
	v_fmac_f32_e32 v108, 0x3e000000, v56
	v_readlane_b32 s21, v254, 34
	v_cndmask_b32_e32 v56, v228, v108, vcc
	s_or_b64 vcc, s[44:45], s[20:21]
	v_readlane_b32 s20, v254, 35
	v_fmac_f32_e32 v109, 0x3e000000, v57
	v_readlane_b32 s21, v254, 36
	v_cndmask_b32_e32 v57, v228, v109, vcc
	s_or_b64 vcc, s[44:45], s[20:21]
	v_readlane_b32 s20, v254, 37
	v_fmac_f32_e32 v110, 0x3e000000, v58
	v_readlane_b32 s21, v254, 38
	v_cndmask_b32_e32 v58, v228, v110, vcc
	s_or_b64 vcc, s[44:45], s[20:21]
	v_readlane_b32 s20, v254, 39
	v_fmac_f32_e32 v111, 0x3e000000, v59
	v_readlane_b32 s21, v254, 40
	s_waitcnt lgkmcnt(0)
	v_cndmask_b32_e32 v59, v228, v111, vcc
	s_or_b64 vcc, s[44:45], s[20:21]
	v_readlane_b32 s20, v254, 41
	v_fmac_f32_e32 v112, 0x3e000000, v60
	v_readlane_b32 s21, v254, 42
	v_max3_f32 v48, v48, v50, v51
	v_cndmask_b32_e32 v100, v228, v112, vcc
	s_or_b64 vcc, s[44:45], s[20:21]
	v_readlane_b32 s20, v254, 43
	v_max3_f32 v48, v48, v52, v53
	v_fmac_f32_e32 v113, 0x3e000000, v61
	v_readlane_b32 s21, v254, 44
	v_max3_f32 v48, v48, v99, v55
	v_cndmask_b32_e32 v101, v228, v113, vcc
	s_or_b64 vcc, s[44:45], s[20:21]
	v_readlane_b32 s20, v254, 45
	v_max3_f32 v48, v48, v56, v57
	v_fmac_f32_e32 v114, 0x3e000000, v62
	v_readlane_b32 s21, v254, 46
	v_max3_f32 v48, v48, v58, v59
	v_cndmask_b32_e32 v62, v228, v114, vcc
	v_fmac_f32_e32 v115, 0x3e000000, v63
	s_or_b64 vcc, s[44:45], s[20:21]
	v_max3_f32 v48, v48, v100, v101
	v_cndmask_b32_e32 v60, v228, v115, vcc
	v_max3_f32 v48, v48, v62, v60
	v_add_u32_e32 v54, 0x8580, v152
	v_add_u32_e32 v108, 0x85a8, v152
	v_add_u32_e32 v61, 0x8588, v152
	v_add_u32_e32 v63, 0x85a0, v152
	ds_read2_b32 v[102:103], v54 offset1:1
	ds_read2_b32 v[104:105], v61 offset1:1
	ds_read2_b32 v[106:107], v63 offset1:1
	ds_read2_b32 v[108:109], v108 offset1:1
	v_readlane_b32 s20, v254, 47
	v_add_u32_e32 v54, 0x85c0, v152
	v_add_u32_e32 v116, 0x85e8, v152
	v_readlane_b32 s21, v254, 48
	v_add_u32_e32 v61, 0x85c8, v152
	v_add_u32_e32 v63, 0x85e0, v152
	ds_read2_b32 v[110:111], v54 offset1:1
	ds_read2_b32 v[112:113], v61 offset1:1
	ds_read2_b32 v[114:115], v63 offset1:1
	ds_read2_b32 v[116:117], v116 offset1:1
	s_waitcnt lgkmcnt(6)
	s_or_b64 vcc, s[44:45], s[20:21]
	v_readlane_b32 s20, v254, 49
	v_fmac_f32_e32 v102, 0x3e000000, v32
	v_readlane_b32 s21, v254, 50
	v_cndmask_b32_e32 v63, v228, v102, vcc
	s_or_b64 vcc, s[44:45], s[20:21]
	v_readlane_b32 s20, v254, 51
	v_fmac_f32_e32 v103, 0x3e000000, v33
	v_readlane_b32 s21, v254, 52
	v_cndmask_b32_e32 v102, v228, v103, vcc
	s_or_b64 vcc, s[44:45], s[20:21]
	v_readlane_b32 s20, v254, 53
	v_fmac_f32_e32 v104, 0x3e000000, v34
	v_readlane_b32 s21, v254, 54
	v_cndmask_b32_e32 v103, v228, v104, vcc
	s_or_b64 vcc, s[44:45], s[20:21]
	v_readlane_b32 s20, v254, 55
	v_fmac_f32_e32 v105, 0x3e000000, v35
	v_readlane_b32 s21, v254, 56
	s_waitcnt lgkmcnt(4)
	v_cndmask_b32_e32 v105, v228, v105, vcc
	s_or_b64 vcc, s[44:45], s[20:21]
	v_readlane_b32 s20, v254, 57
	v_fmac_f32_e32 v106, 0x3e000000, v36
	v_readlane_b32 s21, v254, 58
	v_cndmask_b32_e32 v106, v228, v106, vcc
	s_or_b64 vcc, s[44:45], s[20:21]
	v_readlane_b32 s20, v254, 59
	v_fmac_f32_e32 v107, 0x3e000000, v37
	v_readlane_b32 s21, v254, 60
	v_cndmask_b32_e32 v107, v228, v107, vcc
	s_or_b64 vcc, s[44:45], s[20:21]
	v_readlane_b32 s20, v254, 61
	v_fmac_f32_e32 v108, 0x3e000000, v38
	v_readlane_b32 s21, v254, 62
	v_cndmask_b32_e32 v38, v228, v108, vcc
	s_or_b64 vcc, s[44:45], s[20:21]
	v_readlane_b32 s20, v254, 63
	v_fmac_f32_e32 v109, 0x3e000000, v39
	v_readlane_b32 s21, v255, 0
	s_waitcnt lgkmcnt(2)
	v_cndmask_b32_e32 v118, v228, v109, vcc
	s_or_b64 vcc, s[44:45], s[20:21]
	v_readlane_b32 s20, v255, 1
	v_fmac_f32_e32 v110, 0x3e000000, v40
	v_readlane_b32 s21, v255, 2
	v_cndmask_b32_e32 v110, v228, v110, vcc
	s_or_b64 vcc, s[44:45], s[20:21]
	v_readlane_b32 s20, v255, 3
	v_fmac_f32_e32 v111, 0x3e000000, v41
	v_readlane_b32 s21, v255, 4
	v_cndmask_b32_e32 v119, v228, v111, vcc
	s_or_b64 vcc, s[44:45], s[20:21]
	v_readlane_b32 s20, v255, 5
	v_fmac_f32_e32 v112, 0x3e000000, v42
	v_readlane_b32 s21, v255, 6
	v_cndmask_b32_e32 v112, v228, v112, vcc
	s_or_b64 vcc, s[44:45], s[20:21]
	v_readlane_b32 s20, v255, 7
	v_fmac_f32_e32 v113, 0x3e000000, v43
	v_readlane_b32 s21, v255, 8
	s_waitcnt lgkmcnt(0)
	v_cndmask_b32_e32 v113, v228, v113, vcc
	s_or_b64 vcc, s[44:45], s[20:21]
	v_readlane_b32 s20, v255, 9
	v_max3_f32 v32, v48, v63, v102
	v_fmac_f32_e32 v114, 0x3e000000, v44
	v_readlane_b32 s21, v255, 10
	v_max3_f32 v32, v32, v103, v105
	v_cndmask_b32_e32 v120, v228, v114, vcc
	s_or_b64 vcc, s[44:45], s[20:21]
	v_readlane_b32 s20, v255, 11
	v_max3_f32 v32, v32, v106, v107
	v_fmac_f32_e32 v115, 0x3e000000, v45
	v_readlane_b32 s21, v255, 12
	v_max3_f32 v32, v32, v38, v118
	v_cndmask_b32_e32 v115, v228, v115, vcc
	s_or_b64 vcc, s[44:45], s[20:21]
	v_readlane_b32 s20, v255, 13
	v_max3_f32 v32, v32, v110, v119
	v_fmac_f32_e32 v116, 0x3e000000, v46
	v_readlane_b32 s21, v255, 14
	v_max3_f32 v32, v32, v112, v113
	v_cndmask_b32_e32 v116, v228, v116, vcc
	v_fmac_f32_e32 v117, 0x3e000000, v47
	s_or_b64 vcc, s[44:45], s[20:21]
	v_max3_f32 v32, v32, v120, v115
	v_cndmask_b32_e32 v117, v228, v117, vcc
	v_max3_f32 v39, v32, v116, v117
	v_add_u32_e32 v32, 0x8600, v152
	v_add_u32_e32 v34, 0x8608, v152
	v_add_u32_e32 v36, 0x8620, v152
	v_add_u32_e32 v40, 0x8628, v152
	ds_read2_b32 v[32:33], v32 offset1:1
	ds_read2_b32 v[34:35], v34 offset1:1
	ds_read2_b32 v[36:37], v36 offset1:1
	ds_read2_b32 v[40:41], v40 offset1:1
	v_readlane_b32 s20, v255, 15
	v_add_u32_e32 v42, 0x8640, v152
	v_add_u32_e32 v44, 0x8648, v152
	v_add_u32_e32 v46, 0x8660, v152
	v_readlane_b32 s21, v255, 16
	v_add_u32_e32 v48, 0x8668, v152
	ds_read2_b32 v[42:43], v42 offset1:1
	ds_read2_b32 v[44:45], v44 offset1:1
	ds_read2_b32 v[46:47], v46 offset1:1
	ds_read2_b32 v[108:109], v48 offset1:1
	s_waitcnt lgkmcnt(6)
	s_or_b64 vcc, s[44:45], s[20:21]
	v_readlane_b32 s20, v255, 17
	v_fmac_f32_e32 v32, 0x3e000000, v16
	v_readlane_b32 s21, v255, 18
	v_cndmask_b32_e32 v121, v228, v32, vcc
	s_or_b64 vcc, s[44:45], s[20:21]
	v_readlane_b32 s20, v255, 19
	v_fmac_f32_e32 v33, 0x3e000000, v17
	v_readlane_b32 s21, v255, 20
	v_cndmask_b32_e32 v139, v228, v33, vcc
	s_or_b64 vcc, s[44:45], s[20:21]
	v_readlane_b32 s20, v255, 21
	v_fmac_f32_e32 v34, 0x3e000000, v18
	v_readlane_b32 s21, v255, 22
	v_cndmask_b32_e32 v140, v228, v34, vcc
	s_or_b64 vcc, s[44:45], s[20:21]
	v_readlane_b32 s20, v255, 23
	v_fmac_f32_e32 v35, 0x3e000000, v19
	v_readlane_b32 s21, v255, 24
	s_waitcnt lgkmcnt(4)
	v_cndmask_b32_e32 v141, v228, v35, vcc
	s_or_b64 vcc, s[44:45], s[20:21]
	v_readlane_b32 s20, v255, 25
	v_fmac_f32_e32 v36, 0x3e000000, v20
	v_readlane_b32 s21, v255, 26
	v_cndmask_b32_e32 v167, v228, v36, vcc
	v_fmac_f32_e32 v37, 0x3e000000, v21
	s_or_b64 vcc, s[44:45], s[20:21]
	v_cndmask_b32_e32 v168, v228, v37, vcc
	v_fmac_f32_e32 v40, 0x3e000000, v22
	s_or_b64 vcc, s[44:45], s[58:59]
	s_waitcnt lgkmcnt(2)
	v_cndmask_b32_e32 v169, v228, v40, vcc
	v_fmac_f32_e32 v41, 0x3e000000, v23
	s_or_b64 vcc, s[44:45], s[60:61]
	v_cndmask_b32_e32 v170, v228, v41, vcc
	v_fmac_f32_e32 v42, 0x3e000000, v24
	s_or_b64 vcc, s[44:45], s[62:63]
	v_cndmask_b32_e32 v171, v228, v42, vcc
	v_fmac_f32_e32 v43, 0x3e000000, v25
	s_or_b64 vcc, s[44:45], s[64:65]
	v_max3_f32 v16, v39, v121, v139
	v_cndmask_b32_e32 v172, v228, v43, vcc
	v_fmac_f32_e32 v44, 0x3e000000, v26
	s_or_b64 vcc, s[44:45], s[66:67]
	s_waitcnt lgkmcnt(0)
	v_max3_f32 v16, v16, v140, v141
	v_cndmask_b32_e32 v173, v228, v44, vcc
	v_fmac_f32_e32 v45, 0x3e000000, v27
	s_or_b64 vcc, s[44:45], s[68:69]
	v_max3_f32 v16, v16, v167, v168
	v_cndmask_b32_e32 v174, v228, v45, vcc
	v_fmac_f32_e32 v46, 0x3e000000, v28
	s_or_b64 vcc, s[44:45], s[70:71]
	v_max3_f32 v16, v16, v169, v170
	v_cndmask_b32_e32 v175, v228, v46, vcc
	v_fmac_f32_e32 v47, 0x3e000000, v29
	s_or_b64 vcc, s[44:45], s[72:73]
	v_max3_f32 v16, v16, v171, v172
	v_cndmask_b32_e32 v176, v228, v47, vcc
	v_fmac_f32_e32 v108, 0x3e000000, v30
	s_or_b64 vcc, s[44:45], s[74:75]
	v_max3_f32 v16, v16, v173, v174
	v_cndmask_b32_e32 v108, v228, v108, vcc
	v_fmac_f32_e32 v109, 0x3e000000, v31
	s_or_b64 vcc, s[44:45], s[76:77]
	v_max3_f32 v16, v16, v175, v176
	v_cndmask_b32_e32 v177, v228, v109, vcc
	v_max3_f32 v32, v16, v108, v177
	v_add_u32_e32 v16, 0x8680, v152
	v_add_u32_e32 v18, 0x8688, v152
	v_add_u32_e32 v20, 0x86a0, v152
	v_add_u32_e32 v22, 0x86a8, v152
	ds_read2_b32 v[16:17], v16 offset1:1
	ds_read2_b32 v[18:19], v18 offset1:1
	ds_read2_b32 v[20:21], v20 offset1:1
	ds_read2_b32 v[22:23], v22 offset1:1
	v_add_u32_e32 v24, 0x86c0, v152
	v_add_u32_e32 v26, 0x86c8, v152
	v_add_u32_e32 v28, 0x86e0, v152
	v_add_u32_e32 v30, 0x86e8, v152
	ds_read2_b32 v[24:25], v24 offset1:1
	ds_read2_b32 v[26:27], v26 offset1:1
	ds_read2_b32 v[28:29], v28 offset1:1
	ds_read2_b32 v[30:31], v30 offset1:1
	s_waitcnt lgkmcnt(6)
	s_waitcnt lgkmcnt(4)
	s_waitcnt lgkmcnt(2)
	s_waitcnt lgkmcnt(0)
	v_fmac_f32_e32 v16, 0x3e000000, v0
	v_fmac_f32_e32 v17, 0x3e000000, v1
	v_cndmask_b32_e64 v16, v228, v16, s[78:79]
	v_cndmask_b32_e64 v17, v228, v17, s[80:81]
	v_fmac_f32_e32 v18, 0x3e000000, v2
	v_fmac_f32_e32 v19, 0x3e000000, v3
	v_max3_f32 v0, v32, v16, v17
	v_cndmask_b32_e64 v18, v228, v18, s[82:83]
	v_cndmask_b32_e64 v19, v228, v19, s[84:85]
	v_fmac_f32_e32 v20, 0x3e000000, v4
	v_fmac_f32_e32 v21, 0x3e000000, v5
	v_max3_f32 v0, v0, v18, v19
	v_cndmask_b32_e64 v20, v228, v20, s[86:87]
	v_cndmask_b32_e64 v21, v228, v21, s[88:89]
	v_fmac_f32_e32 v22, 0x3e000000, v6
	v_fmac_f32_e32 v23, 0x3e000000, v7
	v_max3_f32 v0, v0, v20, v21
	v_cndmask_b32_e64 v22, v228, v22, s[90:91]
	v_cndmask_b32_e64 v23, v228, v23, s[92:93]
	v_fmac_f32_e32 v24, 0x3e000000, v8
	v_fmac_f32_e32 v25, 0x3e000000, v9
	v_max3_f32 v0, v0, v22, v23
	v_cndmask_b32_e64 v24, v228, v24, s[94:95]
	v_cndmask_b32_e64 v9, v228, v25, s[96:97]
	v_fmac_f32_e32 v26, 0x3e000000, v10
	v_fmac_f32_e32 v27, 0x3e000000, v11
	v_max3_f32 v0, v0, v24, v9
	v_cndmask_b32_e64 v10, v228, v26, s[2:3]
	v_cndmask_b32_e64 v11, v228, v27, s[4:5]
	v_fmac_f32_e32 v28, 0x3e000000, v12
	v_fmac_f32_e32 v29, 0x3e000000, v13
	v_max3_f32 v0, v0, v10, v11
	v_cndmask_b32_e64 v12, v228, v28, s[6:7]
	v_cndmask_b32_e64 v13, v228, v29, s[8:9]
	v_fmac_f32_e32 v30, 0x3e000000, v14
	v_fmac_f32_e32 v31, 0x3e000000, v15
	v_max3_f32 v0, v0, v12, v13
	v_cndmask_b32_e64 v14, v228, v30, s[10:11]
	v_cndmask_b32_e64 v15, v228, v31, s[12:13]
	v_max3_f32 v0, v0, v14, v15
	ds_bpermute_b32 v1, v234, v0
	s_waitcnt lgkmcnt(0)
	v_max3_f32 v0, v0, v1, v137
	v_sub_f32_e32 v25, v72, v0
	v_mul_f32_e32 v25, 0x3fb8aa3b, v25
	v_exp_f32_e32 v32, v25
	v_sub_f32_e32 v25, v73, v0
	v_mul_f32_e32 v25, 0x3fb8aa3b, v25
	v_exp_f32_e32 v33, v25
	v_sub_f32_e32 v25, v74, v0
	v_mul_f32_e32 v25, 0x3fb8aa3b, v25
	v_exp_f32_e32 v35, v25
	v_sub_f32_e32 v25, v75, v0
	v_mul_f32_e32 v25, 0x3fb8aa3b, v25
	v_sub_f32_e32 v1, v64, v0
	v_exp_f32_e32 v37, v25
	v_sub_f32_e32 v25, v98, v0
	v_sub_f32_e32 v2, v65, v0
	v_mul_f32_e32 v1, 0x3fb8aa3b, v1
	v_mul_f32_e32 v25, 0x3fb8aa3b, v25
	v_sub_f32_e32 v3, v66, v0
	v_mul_f32_e32 v2, 0x3fb8aa3b, v2
	v_exp_f32_e32 v1, v1
	v_exp_f32_e32 v40, v25
	v_sub_f32_e32 v25, v77, v0
	v_exp_f32_e32 v2, v2
	v_mul_f32_e32 v3, 0x3fb8aa3b, v3
	v_sub_f32_e32 v4, v67, v0
	v_mul_f32_e32 v25, 0x3fb8aa3b, v25
	v_exp_f32_e32 v3, v3
	v_mul_f32_e32 v4, 0x3fb8aa3b, v4
	v_sub_f32_e32 v5, v68, v0
	v_exp_f32_e32 v45, v25
	v_sub_f32_e32 v25, v78, v0
	v_exp_f32_e32 v4, v4
	v_mul_f32_e32 v5, 0x3fb8aa3b, v5
	v_sub_f32_e32 v6, v69, v0
	v_mul_f32_e32 v25, 0x3fb8aa3b, v25
	v_exp_f32_e32 v5, v5
	v_mul_f32_e32 v6, 0x3fb8aa3b, v6
	v_sub_f32_e32 v7, v70, v0
	v_exp_f32_e32 v48, v25
	v_add_f32_e32 v25, 0, v1
	v_exp_f32_e32 v6, v6
	v_mul_f32_e32 v7, 0x3fb8aa3b, v7
	v_sub_f32_e32 v8, v71, v0
	v_add_f32_e32 v25, v2, v25
	v_exp_f32_e32 v7, v7
	v_mul_f32_e32 v8, 0x3fb8aa3b, v8
	v_add_f32_e32 v25, v3, v25
	v_exp_f32_e32 v8, v8
	v_add_f32_e32 v25, v4, v25
	v_add_f32_e32 v25, v5, v25
	v_add_f32_e32 v25, v6, v25
	v_add_f32_e32 v25, v7, v25
	v_add_f32_e32 v25, v8, v25
	v_add_f32_e32 v25, v32, v25
	v_add_f32_e32 v25, v33, v25
	v_sub_f32_e32 v26, v76, v0
	v_add_f32_e32 v25, v35, v25
	v_mul_f32_e32 v26, 0x3fb8aa3b, v26
	v_add_f32_e32 v25, v37, v25
	v_exp_f32_e32 v109, v26
	v_add_f32_e32 v25, v40, v25
	v_add_f32_e32 v25, v45, v25
	v_add_f32_e32 v25, v48, v25
	v_add_f32_e32 v25, v109, v25
	v_sub_f32_e32 v26, v79, v0
	v_mul_f32_e32 v26, 0x3fb8aa3b, v26
	v_exp_f32_e32 v42, v26
	v_sub_f32_e32 v26, v49, v0
	v_mul_f32_e32 v26, 0x3fb8aa3b, v26
	v_exp_f32_e32 v49, v26
	v_sub_f32_e32 v26, v50, v0
	v_mul_f32_e32 v26, 0x3fb8aa3b, v26
	v_exp_f32_e32 v54, v26
	v_sub_f32_e32 v26, v51, v0
	v_mul_f32_e32 v26, 0x3fb8aa3b, v26
	v_exp_f32_e32 v61, v26
	v_sub_f32_e32 v26, v52, v0
	v_mul_f32_e32 v26, 0x3fb8aa3b, v26
	v_exp_f32_e32 v67, v26
	v_sub_f32_e32 v26, v53, v0
	v_mul_f32_e32 v26, 0x3fb8aa3b, v26
	v_exp_f32_e32 v74, v26
	v_sub_f32_e32 v26, v99, v0
	v_mul_f32_e32 v26, 0x3fb8aa3b, v26
	v_exp_f32_e32 v79, v26
	v_sub_f32_e32 v26, v55, v0
	v_mul_f32_e32 v26, 0x3fb8aa3b, v26
	v_exp_f32_e32 v104, v26
	v_sub_f32_e32 v26, v56, v0
	v_mul_f32_e32 v26, 0x3fb8aa3b, v26
	v_exp_f32_e32 v34, v26
	v_sub_f32_e32 v26, v57, v0
	v_mul_f32_e32 v26, 0x3fb8aa3b, v26
	v_exp_f32_e32 v36, v26
	v_sub_f32_e32 v26, v58, v0
	v_mul_f32_e32 v26, 0x3fb8aa3b, v26
	v_add_f32_e32 v25, v42, v25
	v_exp_f32_e32 v39, v26
	v_sub_f32_e32 v26, v59, v0
	v_add_f32_e32 v25, v49, v25
	v_mul_f32_e32 v26, 0x3fb8aa3b, v26
	v_add_f32_e32 v25, v54, v25
	v_exp_f32_e32 v43, v26
	v_sub_f32_e32 v26, v100, v0
	v_add_f32_e32 v25, v61, v25
	v_mul_f32_e32 v26, 0x3fb8aa3b, v26
	v_add_f32_e32 v25, v67, v25
	v_exp_f32_e32 v47, v26
	v_sub_f32_e32 v26, v101, v0
	v_add_f32_e32 v25, v74, v25
	v_mul_f32_e32 v26, 0x3fb8aa3b, v26
	v_add_f32_e32 v25, v79, v25
	v_exp_f32_e32 v55, v26
	v_sub_f32_e32 v26, v62, v0
	v_add_f32_e32 v25, v104, v25
	v_mul_f32_e32 v26, 0x3fb8aa3b, v26
	v_add_f32_e32 v25, v34, v25
	v_exp_f32_e32 v58, v26
	v_add_f32_e32 v25, v36, v25
	v_sub_f32_e32 v26, v60, v0
	v_add_f32_e32 v25, v39, v25
	v_mul_f32_e32 v26, 0x3fb8aa3b, v26
	v_add_f32_e32 v25, v43, v25
	v_exp_f32_e32 v114, v26
	v_add_f32_e32 v25, v47, v25
	v_add_f32_e32 v25, v55, v25
	v_add_f32_e32 v25, v58, v25
	v_add_f32_e32 v25, v114, v25
	v_sub_f32_e32 v26, v63, v0
	v_mul_f32_e32 v26, 0x3fb8aa3b, v26
	v_exp_f32_e32 v51, v26
	v_sub_f32_e32 v26, v102, v0
	v_mul_f32_e32 v26, 0x3fb8aa3b, v26
	v_exp_f32_e32 v59, v26
	v_sub_f32_e32 v26, v103, v0
	v_mul_f32_e32 v26, 0x3fb8aa3b, v26
	v_exp_f32_e32 v64, v26
	v_sub_f32_e32 v26, v105, v0
	v_mul_f32_e32 v26, 0x3fb8aa3b, v26
	v_exp_f32_e32 v71, v26
	v_sub_f32_e32 v26, v106, v0
	v_mul_f32_e32 v26, 0x3fb8aa3b, v26
	v_exp_f32_e32 v77, v26
	v_sub_f32_e32 v26, v107, v0
	v_mul_f32_e32 v26, 0x3fb8aa3b, v26
	v_exp_f32_e32 v101, v26
	v_sub_f32_e32 v26, v38, v0
	v_mul_f32_e32 v26, 0x3fb8aa3b, v26
	v_exp_f32_e32 v106, v26
	v_sub_f32_e32 v26, v118, v0
	v_mul_f32_e32 v26, 0x3fb8aa3b, v26
	v_exp_f32_e32 v111, v26
	v_sub_f32_e32 v26, v110, v0
	v_mul_f32_e32 v26, 0x3fb8aa3b, v26
	v_exp_f32_e32 v38, v26
	v_sub_f32_e32 v26, v119, v0
	v_mul_f32_e32 v26, 0x3fb8aa3b, v26
	v_exp_f32_e32 v41, v26
	v_sub_f32_e32 v26, v112, v0
	v_mul_f32_e32 v26, 0x3fb8aa3b, v26
	v_add_f32_e32 v25, v51, v25
	v_exp_f32_e32 v46, v26
	v_sub_f32_e32 v26, v113, v0
	v_add_f32_e32 v25, v59, v25
	v_mul_f32_e32 v26, 0x3fb8aa3b, v26
	v_add_f32_e32 v25, v64, v25
	v_exp_f32_e32 v52, v26
	v_sub_f32_e32 v26, v120, v0
	v_add_f32_e32 v25, v71, v25
	v_mul_f32_e32 v26, 0x3fb8aa3b, v26
	v_add_f32_e32 v25, v77, v25
	v_exp_f32_e32 v57, v26
	v_sub_f32_e32 v26, v115, v0
	v_add_f32_e32 v25, v101, v25
	v_mul_f32_e32 v26, 0x3fb8aa3b, v26
	v_add_f32_e32 v25, v106, v25
	v_exp_f32_e32 v65, v26
	v_sub_f32_e32 v26, v116, v0
	v_add_f32_e32 v25, v111, v25
	v_mul_f32_e32 v26, 0x3fb8aa3b, v26
	v_add_f32_e32 v25, v38, v25
	v_exp_f32_e32 v69, v26
	v_add_f32_e32 v25, v41, v25
	v_sub_f32_e32 v26, v117, v0
	v_add_f32_e32 v25, v46, v25
	v_mul_f32_e32 v26, 0x3fb8aa3b, v26
	v_add_f32_e32 v25, v52, v25
	v_exp_f32_e32 v118, v26
	v_add_f32_e32 v25, v57, v25
	v_add_f32_e32 v25, v65, v25
	v_add_f32_e32 v25, v69, v25
	v_add_f32_e32 v25, v118, v25
	v_sub_f32_e32 v26, v121, v0
	v_mul_f32_e32 v26, 0x3fb8aa3b, v26
	v_exp_f32_e32 v62, v26
	v_sub_f32_e32 v26, v139, v0
	v_mul_f32_e32 v26, 0x3fb8aa3b, v26
	v_exp_f32_e32 v70, v26
	v_sub_f32_e32 v26, v140, v0
	v_mul_f32_e32 v26, 0x3fb8aa3b, v26
	v_exp_f32_e32 v75, v26
	v_sub_f32_e32 v26, v141, v0
	v_mul_f32_e32 v26, 0x3fb8aa3b, v26
	v_exp_f32_e32 v100, v26
	v_sub_f32_e32 v26, v167, v0
	v_mul_f32_e32 v26, 0x3fb8aa3b, v26
	v_exp_f32_e32 v105, v26
	v_sub_f32_e32 v26, v168, v0
	v_mul_f32_e32 v26, 0x3fb8aa3b, v26
	v_exp_f32_e32 v110, v26
	v_sub_f32_e32 v26, v169, v0
	v_mul_f32_e32 v26, 0x3fb8aa3b, v26
	v_exp_f32_e32 v113, v26
	v_sub_f32_e32 v26, v170, v0
	v_mul_f32_e32 v26, 0x3fb8aa3b, v26
	v_exp_f32_e32 v116, v26
	v_sub_f32_e32 v26, v171, v0
	v_mul_f32_e32 v26, 0x3fb8aa3b, v26
	v_exp_f32_e32 v44, v26
	v_sub_f32_e32 v26, v172, v0
	v_mul_f32_e32 v26, 0x3fb8aa3b, v26
	v_exp_f32_e32 v50, v26
	v_sub_f32_e32 v26, v173, v0
	v_mul_f32_e32 v26, 0x3fb8aa3b, v26
	v_add_f32_e32 v25, v62, v25
	v_exp_f32_e32 v56, v26
	v_sub_f32_e32 v26, v174, v0
	v_add_f32_e32 v25, v70, v25
	v_mul_f32_e32 v26, 0x3fb8aa3b, v26
	v_add_f32_e32 v25, v75, v25
	v_exp_f32_e32 v63, v26
	v_sub_f32_e32 v26, v175, v0
	v_add_f32_e32 v25, v100, v25
	v_mul_f32_e32 v26, 0x3fb8aa3b, v26
	v_add_f32_e32 v25, v105, v25
	v_exp_f32_e32 v68, v26
	v_sub_f32_e32 v26, v176, v0
	v_add_f32_e32 v25, v110, v25
	v_mul_f32_e32 v26, 0x3fb8aa3b, v26
	v_add_f32_e32 v25, v113, v25
	v_exp_f32_e32 v76, v26
	v_sub_f32_e32 v26, v108, v0
	v_add_f32_e32 v25, v116, v25
	v_mul_f32_e32 v26, 0x3fb8aa3b, v26
	v_add_f32_e32 v25, v44, v25
	v_exp_f32_e32 v98, v26
	v_add_f32_e32 v25, v50, v25
	v_sub_f32_e32 v26, v177, v0
	v_add_f32_e32 v25, v56, v25
	v_mul_f32_e32 v26, 0x3fb8aa3b, v26
	v_add_f32_e32 v25, v63, v25
	v_exp_f32_e32 v120, v26
	v_add_f32_e32 v25, v68, v25
	v_add_f32_e32 v25, v76, v25
	v_add_f32_e32 v25, v98, v25
	v_add_f32_e32 v25, v120, v25
	v_sub_f32_e32 v16, v16, v0
	v_mul_f32_e32 v16, 0x3fb8aa3b, v16
	v_exp_f32_e32 v72, v16
	v_sub_f32_e32 v16, v17, v0
	v_sub_f32_e32 v9, v9, v0
	v_mul_f32_e32 v16, 0x3fb8aa3b, v16
	v_mul_f32_e32 v9, 0x3fb8aa3b, v9
	v_exp_f32_e32 v99, v16
	v_sub_f32_e32 v16, v18, v0
	v_exp_f32_e32 v60, v9
	v_sub_f32_e32 v9, v10, v0
	v_mul_f32_e32 v16, 0x3fb8aa3b, v16
	v_mul_f32_e32 v9, 0x3fb8aa3b, v9
	v_exp_f32_e32 v102, v16
	v_sub_f32_e32 v16, v19, v0
	v_exp_f32_e32 v66, v9
	v_sub_f32_e32 v9, v11, v0
	v_mul_f32_e32 v16, 0x3fb8aa3b, v16
	v_mul_f32_e32 v9, 0x3fb8aa3b, v9
	v_exp_f32_e32 v108, v16
	v_sub_f32_e32 v16, v20, v0
	v_exp_f32_e32 v73, v9
	v_sub_f32_e32 v9, v12, v0
	v_mul_f32_e32 v16, 0x3fb8aa3b, v16
	v_mul_f32_e32 v9, 0x3fb8aa3b, v9
	v_exp_f32_e32 v112, v16
	v_sub_f32_e32 v16, v21, v0
	v_exp_f32_e32 v78, v9
	v_sub_f32_e32 v9, v13, v0
	v_mul_f32_e32 v16, 0x3fb8aa3b, v16
	v_mul_f32_e32 v9, 0x3fb8aa3b, v9
	v_exp_f32_e32 v115, v16
	v_sub_f32_e32 v16, v22, v0
	v_exp_f32_e32 v103, v9
	v_sub_f32_e32 v9, v14, v0
	v_mul_f32_e32 v16, 0x3fb8aa3b, v16
	v_mul_f32_e32 v9, 0x3fb8aa3b, v9
	v_exp_f32_e32 v117, v16
	v_sub_f32_e32 v16, v23, v0
	v_exp_f32_e32 v107, v9
	v_add_f32_e32 v9, v72, v25
	v_mul_f32_e32 v16, 0x3fb8aa3b, v16
	v_add_f32_e32 v9, v99, v9
	v_exp_f32_e32 v119, v16
	v_sub_f32_e32 v16, v24, v0
	v_add_f32_e32 v9, v102, v9
	v_mul_f32_e32 v16, 0x3fb8aa3b, v16
	v_add_f32_e32 v9, v108, v9
	v_exp_f32_e32 v53, v16
	v_add_f32_e32 v9, v112, v9
	v_add_f32_e32 v9, v115, v9
	v_add_f32_e32 v9, v117, v9
	v_add_f32_e32 v9, v119, v9
	v_add_f32_e32 v9, v53, v9
	v_add_f32_e32 v9, v60, v9
	v_sub_f32_e32 v10, v15, v0
	v_add_f32_e32 v9, v66, v9
	v_mul_f32_e32 v10, 0x3fb8aa3b, v10
	v_add_f32_e32 v9, v73, v9
	v_exp_f32_e32 v121, v10
	v_add_f32_e32 v9, v78, v9
	v_add_f32_e32 v9, v103, v9
	v_add_f32_e32 v9, v107, v9
	v_add_f32_e32 v9, v121, v9
	ds_bpermute_b32 v10, v234, v9
	s_and_saveexec_b64 s[20:21], s[14:15]
	s_cbranch_execz .LBB0_470
	s_mov_b32 s23, 0x1000706
	s_waitcnt vmcnt(0)
	v_perm_b32 v11, v94, v95, s23
	v_perm_b32 v95, v95, v96, s23
	v_perm_b32 v96, v96, v97, s23
	v_perm_b32 v97, v97, v94, s23
	v_mov_b32_e32 v94, v11
